# v42 + GEMM1 epilogues aligned between the wave halves only for the conv tiles (which exchange rows through LDS under a barrier); og / gate / q|k / v tiles run unaligned
# baseline (speedup 1.0000x reference)
.LBB0_228:
	ds_read_b128 v[128:131], v179
	ds_read_b128 v[132:135], v179 offset:1024
	ds_read_b128 v[136:139], v179 offset:2048
	ds_read_b128 v[140:143], v179 offset:3072
	ds_read_b128 v[162:165], v180
	ds_read_b128 v[166:169], v180 offset:1024
	ds_read_b128 v[170:173], v180 offset:2048
	ds_read_b128 v[186:189], v180 offset:3072
	s_add_u32 s8, s6, 0x10000
	s_addc_u32 s9, s7, 0
	s_cmp_eq_u32 s92, 12
	s_cselect_b32 s80, s69, s8
	s_cselect_b32 s81, s18, s9
	s_cselect_b32 s12, s77, vcc_lo
	s_cselect_b32 s13, s71, vcc_hi
	s_add_u32 s10, s80, 0x8000
	s_addc_u32 s11, s81, 0
	s_add_i32 m0, s79, 0xc000
	ds_read_b128 v[190:193], v181
	ds_read_b128 v[194:197], v181 offset:1024
	ds_read_b128 v[198:201], v181 offset:2048
	ds_read_b128 v[202:205], v181 offset:3072
	ds_read_b128 v[206:209], v181 offset:4096
	ds_read_b128 v[210:213], v181 offset:5120
	ds_read_b128 v[214:217], v181 offset:6144
	ds_read_b128 v[218:221], v181 offset:7168
	global_load_lds_dwordx4 v154, s[6:7]
	s_add_i32 m0, s79, 0xe000
	s_nop 0
	global_load_lds_dwordx4 v156, s[6:7]
	s_waitcnt vmcnt(8)
	s_waitcnt lgkmcnt(0)
	s_barrier
	s_setprio 1
	s_waitcnt lgkmcnt(0)
	v_mfma_f32_16x16x32_bf16 v[124:127], v[128:131], v[190:193], v[124:127]
	v_mfma_f32_16x16x32_bf16 v[120:123], v[136:139], v[190:193], v[120:123]
	v_mfma_f32_16x16x32_bf16 v[108:111], v[128:131], v[198:201], v[108:111]
	v_mfma_f32_16x16x32_bf16 v[104:107], v[136:139], v[198:201], v[104:107]
	v_mfma_f32_16x16x32_bf16 v[92:95], v[128:131], v[206:209], v[92:95]
	v_mfma_f32_16x16x32_bf16 v[88:91], v[136:139], v[206:209], v[88:91]
	v_mfma_f32_16x16x32_bf16 v[76:79], v[128:131], v[214:217], v[76:79]
	v_mfma_f32_16x16x32_bf16 v[72:75], v[136:139], v[214:217], v[72:75]
	v_mfma_f32_16x16x32_bf16 v[124:127], v[132:135], v[194:197], v[124:127]
	v_mfma_f32_16x16x32_bf16 v[120:123], v[140:143], v[194:197], v[120:123]
	v_mfma_f32_16x16x32_bf16 v[108:111], v[132:135], v[202:205], v[108:111]
	v_mfma_f32_16x16x32_bf16 v[104:107], v[140:143], v[202:205], v[104:107]
	v_mfma_f32_16x16x32_bf16 v[92:95], v[132:135], v[210:213], v[92:95]
	v_mfma_f32_16x16x32_bf16 v[88:91], v[140:143], v[210:213], v[88:91]
	v_mfma_f32_16x16x32_bf16 v[76:79], v[132:135], v[218:221], v[76:79]
	v_mfma_f32_16x16x32_bf16 v[72:75], v[140:143], v[218:221], v[72:75]
	s_setprio 0
	s_setprio 1
	v_mfma_f32_16x16x32_bf16 v[116:119], v[162:165], v[190:193], v[116:119]
	v_mfma_f32_16x16x32_bf16 v[112:115], v[170:173], v[190:193], v[112:115]
	v_mfma_f32_16x16x32_bf16 v[100:103], v[162:165], v[198:201], v[100:103]
	v_mfma_f32_16x16x32_bf16 v[96:99], v[170:173], v[198:201], v[96:99]
	v_mfma_f32_16x16x32_bf16 v[84:87], v[162:165], v[206:209], v[84:87]
	v_mfma_f32_16x16x32_bf16 v[80:83], v[170:173], v[206:209], v[80:83]
	v_mfma_f32_16x16x32_bf16 v[68:71], v[162:165], v[214:217], v[68:71]
	v_mfma_f32_16x16x32_bf16 v[64:67], v[170:173], v[214:217], v[64:67]
	v_mfma_f32_16x16x32_bf16 v[116:119], v[166:169], v[194:197], v[116:119]
	v_mfma_f32_16x16x32_bf16 v[112:115], v[186:189], v[194:197], v[112:115]
	v_mfma_f32_16x16x32_bf16 v[100:103], v[166:169], v[202:205], v[100:103]
	v_mfma_f32_16x16x32_bf16 v[96:99], v[186:189], v[202:205], v[96:99]
	v_mfma_f32_16x16x32_bf16 v[84:87], v[166:169], v[210:213], v[84:87]
	v_mfma_f32_16x16x32_bf16 v[80:83], v[186:189], v[210:213], v[80:83]
	v_mfma_f32_16x16x32_bf16 v[68:71], v[166:169], v[218:221], v[68:71]
	v_mfma_f32_16x16x32_bf16 v[64:67], v[186:189], v[218:221], v[64:67]
	s_setprio 0
	s_barrier
	s_add_i32 s6, s34, s84
	s_mov_b32 m0, s6
	ds_read_b128 v[190:193], v181 offset:16384
	ds_read_b128 v[194:197], v181 offset:17408
	ds_read_b128 v[198:201], v181 offset:18432
	ds_read_b128 v[202:205], v181 offset:19456
	ds_read_b128 v[206:209], v181 offset:20480
	ds_read_b128 v[210:213], v181 offset:21504
	ds_read_b128 v[214:217], v181 offset:22528
	ds_read_b128 v[218:221], v181 offset:23552
	global_load_lds_dwordx4 v146, s[12:13]
	s_add_i32 m0, s6, 0x2000
	s_add_u32 s6, s12, 0x40000
	s_addc_u32 s7, s13, 0
	s_add_i32 s38, s35, s84
	global_load_lds_dwordx4 v150, s[12:13]
	s_mov_b32 m0, s38
	s_nop 0
	global_load_lds_dwordx4 v146, s[6:7]
	s_add_i32 m0, s38, 0x2000
	s_nop 0
	global_load_lds_dwordx4 v150, s[6:7]
	s_mov_b32 m0, s79
	s_nop 0
	global_load_lds_dwordx4 v144, s[80:81]
	s_mov_b32 m0, s85
	s_nop 0
	global_load_lds_dwordx4 v148, s[80:81]
	s_waitcnt vmcnt(8)
	s_waitcnt lgkmcnt(0)
	s_barrier
	s_setprio 1
	s_waitcnt lgkmcnt(0)
	v_mfma_f32_16x16x32_bf16 v[60:63], v[128:131], v[190:193], v[60:63]
	v_mfma_f32_16x16x32_bf16 v[56:59], v[136:139], v[190:193], v[56:59]
	v_mfma_f32_16x16x32_bf16 v[44:47], v[128:131], v[198:201], v[44:47]
	v_mfma_f32_16x16x32_bf16 v[40:43], v[136:139], v[198:201], v[40:43]
	v_mfma_f32_16x16x32_bf16 v[28:31], v[128:131], v[206:209], v[28:31]
	v_mfma_f32_16x16x32_bf16 v[24:27], v[136:139], v[206:209], v[24:27]
	v_mfma_f32_16x16x32_bf16 v[12:15], v[128:131], v[214:217], v[12:15]
	v_mfma_f32_16x16x32_bf16 v[8:11], v[136:139], v[214:217], v[8:11]
	v_mfma_f32_16x16x32_bf16 v[60:63], v[132:135], v[194:197], v[60:63]
	v_mfma_f32_16x16x32_bf16 v[56:59], v[140:143], v[194:197], v[56:59]
	v_mfma_f32_16x16x32_bf16 v[44:47], v[132:135], v[202:205], v[44:47]
	v_mfma_f32_16x16x32_bf16 v[40:43], v[140:143], v[202:205], v[40:43]
	v_mfma_f32_16x16x32_bf16 v[28:31], v[132:135], v[210:213], v[28:31]
	v_mfma_f32_16x16x32_bf16 v[24:27], v[140:143], v[210:213], v[24:27]
	v_mfma_f32_16x16x32_bf16 v[12:15], v[132:135], v[218:221], v[12:15]
	v_mfma_f32_16x16x32_bf16 v[8:11], v[140:143], v[218:221], v[8:11]
	s_setprio 0
	s_setprio 1
	v_mfma_f32_16x16x32_bf16 v[52:55], v[162:165], v[190:193], v[52:55]
	v_mfma_f32_16x16x32_bf16 v[48:51], v[170:173], v[190:193], v[48:51]
	v_mfma_f32_16x16x32_bf16 v[36:39], v[162:165], v[198:201], v[36:39]
	v_mfma_f32_16x16x32_bf16 v[32:35], v[170:173], v[198:201], v[32:35]
	v_mfma_f32_16x16x32_bf16 v[20:23], v[162:165], v[206:209], v[20:23]
	v_mfma_f32_16x16x32_bf16 v[16:19], v[170:173], v[206:209], v[16:19]
	v_mfma_f32_16x16x32_bf16 v[4:7], v[162:165], v[214:217], v[4:7]
	v_mfma_f32_16x16x32_bf16 v[0:3], v[170:173], v[214:217], v[0:3]
	v_mfma_f32_16x16x32_bf16 v[52:55], v[166:169], v[194:197], v[52:55]
	v_mfma_f32_16x16x32_bf16 v[48:51], v[186:189], v[194:197], v[48:51]
	v_mfma_f32_16x16x32_bf16 v[36:39], v[166:169], v[202:205], v[36:39]
	v_mfma_f32_16x16x32_bf16 v[32:35], v[186:189], v[202:205], v[32:35]
	v_mfma_f32_16x16x32_bf16 v[20:23], v[166:169], v[210:213], v[20:23]
	v_mfma_f32_16x16x32_bf16 v[16:19], v[186:189], v[210:213], v[16:19]
	v_mfma_f32_16x16x32_bf16 v[4:7], v[166:169], v[218:221], v[4:7]
	v_mfma_f32_16x16x32_bf16 v[0:3], v[186:189], v[218:221], v[0:3]
	s_setprio 0
	s_barrier
	s_add_i32 s38, 0, 0x18000
	s_add_i32 s39, 0, 0x1c000
	v_add_u32_e32 v140, s38, v178
	v_add_u32_e32 v152, s39, v178
	ds_read_b128 v[128:131], v140
	ds_read_b128 v[132:135], v140 offset:1024
	ds_read_b128 v[136:139], v140 offset:2048
	ds_read_b128 v[140:143], v140 offset:3072
	ds_read_b128 v[162:165], v152
	ds_read_b128 v[166:169], v152 offset:1024
	ds_read_b128 v[170:173], v152 offset:2048
	ds_read_b128 v[186:189], v152 offset:3072
	s_add_u32 s6, s80, 0x4000
	s_addc_u32 s7, s81, 0
	s_mov_b32 m0, s86
	ds_read_b128 v[190:193], v181 offset:32768
	ds_read_b128 v[194:197], v181 offset:33792
	ds_read_b128 v[198:201], v181 offset:34816
	ds_read_b128 v[202:205], v181 offset:35840
	ds_read_b128 v[206:209], v181 offset:36864
	ds_read_b128 v[210:213], v181 offset:37888
	ds_read_b128 v[214:217], v181 offset:38912
	ds_read_b128 v[218:221], v181 offset:39936
	global_load_lds_dwordx4 v144, s[6:7]
	s_mov_b32 m0, s87
	s_nop 0
	global_load_lds_dwordx4 v148, s[6:7]
	s_waitcnt vmcnt(8)
	s_waitcnt lgkmcnt(0)
	s_barrier
	s_setprio 1
	s_waitcnt lgkmcnt(0)
	v_mfma_f32_16x16x32_bf16 v[124:127], v[128:131], v[190:193], v[124:127]
	v_mfma_f32_16x16x32_bf16 v[120:123], v[136:139], v[190:193], v[120:123]
	v_mfma_f32_16x16x32_bf16 v[108:111], v[128:131], v[198:201], v[108:111]
	v_mfma_f32_16x16x32_bf16 v[104:107], v[136:139], v[198:201], v[104:107]
	v_mfma_f32_16x16x32_bf16 v[92:95], v[128:131], v[206:209], v[92:95]
	v_mfma_f32_16x16x32_bf16 v[88:91], v[136:139], v[206:209], v[88:91]
	v_mfma_f32_16x16x32_bf16 v[76:79], v[128:131], v[214:217], v[76:79]
	v_mfma_f32_16x16x32_bf16 v[72:75], v[136:139], v[214:217], v[72:75]
	v_mfma_f32_16x16x32_bf16 v[124:127], v[132:135], v[194:197], v[124:127]
	v_mfma_f32_16x16x32_bf16 v[120:123], v[140:143], v[194:197], v[120:123]
	v_mfma_f32_16x16x32_bf16 v[108:111], v[132:135], v[202:205], v[108:111]
	v_mfma_f32_16x16x32_bf16 v[104:107], v[140:143], v[202:205], v[104:107]
	v_mfma_f32_16x16x32_bf16 v[92:95], v[132:135], v[210:213], v[92:95]
	v_mfma_f32_16x16x32_bf16 v[88:91], v[140:143], v[210:213], v[88:91]
	v_mfma_f32_16x16x32_bf16 v[76:79], v[132:135], v[218:221], v[76:79]
	v_mfma_f32_16x16x32_bf16 v[72:75], v[140:143], v[218:221], v[72:75]
	s_setprio 0
	s_setprio 1
	v_mfma_f32_16x16x32_bf16 v[116:119], v[162:165], v[190:193], v[116:119]
	v_mfma_f32_16x16x32_bf16 v[112:115], v[170:173], v[190:193], v[112:115]
	v_mfma_f32_16x16x32_bf16 v[100:103], v[162:165], v[198:201], v[100:103]
	v_mfma_f32_16x16x32_bf16 v[96:99], v[170:173], v[198:201], v[96:99]
	v_mfma_f32_16x16x32_bf16 v[84:87], v[162:165], v[206:209], v[84:87]
	v_mfma_f32_16x16x32_bf16 v[80:83], v[170:173], v[206:209], v[80:83]
	v_mfma_f32_16x16x32_bf16 v[68:71], v[162:165], v[214:217], v[68:71]
	v_mfma_f32_16x16x32_bf16 v[64:67], v[170:173], v[214:217], v[64:67]
	v_mfma_f32_16x16x32_bf16 v[116:119], v[166:169], v[194:197], v[116:119]
	v_mfma_f32_16x16x32_bf16 v[112:115], v[186:189], v[194:197], v[112:115]
	v_mfma_f32_16x16x32_bf16 v[100:103], v[166:169], v[202:205], v[100:103]
	v_mfma_f32_16x16x32_bf16 v[96:99], v[186:189], v[202:205], v[96:99]
	v_mfma_f32_16x16x32_bf16 v[84:87], v[166:169], v[210:213], v[84:87]
	v_mfma_f32_16x16x32_bf16 v[80:83], v[186:189], v[210:213], v[80:83]
	v_mfma_f32_16x16x32_bf16 v[68:71], v[166:169], v[218:221], v[68:71]
	v_mfma_f32_16x16x32_bf16 v[64:67], v[186:189], v[218:221], v[64:67]
	s_setprio 0
	s_barrier
	s_add_u32 s98, s12, s48
	s_addc_u32 s99, s13, s49
	s_add_i32 s6, s38, s84
	s_mov_b32 m0, s6
	ds_read_b128 v[190:193], v181 offset:49152
	ds_read_b128 v[194:197], v181 offset:50176
	ds_read_b128 v[198:201], v181 offset:51200
	ds_read_b128 v[202:205], v181 offset:52224
	ds_read_b128 v[206:209], v181 offset:53248
	ds_read_b128 v[210:213], v181 offset:54272
	ds_read_b128 v[214:217], v181 offset:55296
	ds_read_b128 v[218:221], v181 offset:56320
	global_load_lds_dwordx4 v146, s[98:99]
	s_add_i32 m0, s6, 0x2000
	s_add_u32 s6, s12, 0x40080
	s_addc_u32 s7, s13, 0
	s_add_i32 s12, s39, s84
	global_load_lds_dwordx4 v150, s[98:99]
	s_mov_b32 m0, s12
	s_nop 0
	global_load_lds_dwordx4 v146, s[6:7]
	s_add_i32 m0, s12, 0x2000
	s_nop 0
	global_load_lds_dwordx4 v150, s[6:7]
	s_mov_b32 m0, s33
	s_nop 0
	global_load_lds_dwordx4 v144, s[10:11]
	s_mov_b32 m0, s56
	s_nop 0
	global_load_lds_dwordx4 v148, s[10:11]
	s_waitcnt vmcnt(8)
	s_waitcnt lgkmcnt(0)
	s_barrier
	s_setprio 1
	s_waitcnt lgkmcnt(0)
	v_mfma_f32_16x16x32_bf16 v[60:63], v[128:131], v[190:193], v[60:63]
	v_mfma_f32_16x16x32_bf16 v[56:59], v[136:139], v[190:193], v[56:59]
	v_mfma_f32_16x16x32_bf16 v[44:47], v[128:131], v[198:201], v[44:47]
	v_mfma_f32_16x16x32_bf16 v[40:43], v[136:139], v[198:201], v[40:43]
	v_mfma_f32_16x16x32_bf16 v[28:31], v[128:131], v[206:209], v[28:31]
	v_mfma_f32_16x16x32_bf16 v[24:27], v[136:139], v[206:209], v[24:27]
	v_mfma_f32_16x16x32_bf16 v[12:15], v[128:131], v[214:217], v[12:15]
	v_mfma_f32_16x16x32_bf16 v[8:11], v[136:139], v[214:217], v[8:11]
	v_mfma_f32_16x16x32_bf16 v[60:63], v[132:135], v[194:197], v[60:63]
	v_mfma_f32_16x16x32_bf16 v[56:59], v[140:143], v[194:197], v[56:59]
	v_mfma_f32_16x16x32_bf16 v[44:47], v[132:135], v[202:205], v[44:47]
	v_mfma_f32_16x16x32_bf16 v[40:43], v[140:143], v[202:205], v[40:43]
	v_mfma_f32_16x16x32_bf16 v[28:31], v[132:135], v[210:213], v[28:31]
	v_mfma_f32_16x16x32_bf16 v[24:27], v[140:143], v[210:213], v[24:27]
	v_mfma_f32_16x16x32_bf16 v[12:15], v[132:135], v[218:221], v[12:15]
	v_mfma_f32_16x16x32_bf16 v[8:11], v[140:143], v[218:221], v[8:11]
	s_setprio 0
	s_setprio 1
	v_mfma_f32_16x16x32_bf16 v[52:55], v[162:165], v[190:193], v[52:55]
	v_mfma_f32_16x16x32_bf16 v[48:51], v[170:173], v[190:193], v[48:51]
	v_mfma_f32_16x16x32_bf16 v[36:39], v[162:165], v[198:201], v[36:39]
	v_mfma_f32_16x16x32_bf16 v[32:35], v[170:173], v[198:201], v[32:35]
	v_mfma_f32_16x16x32_bf16 v[20:23], v[162:165], v[206:209], v[20:23]
	v_mfma_f32_16x16x32_bf16 v[16:19], v[170:173], v[206:209], v[16:19]
	v_mfma_f32_16x16x32_bf16 v[4:7], v[162:165], v[214:217], v[4:7]
	v_mfma_f32_16x16x32_bf16 v[0:3], v[170:173], v[214:217], v[0:3]
	v_mfma_f32_16x16x32_bf16 v[52:55], v[166:169], v[194:197], v[52:55]
	v_mfma_f32_16x16x32_bf16 v[48:51], v[186:189], v[194:197], v[48:51]
	v_mfma_f32_16x16x32_bf16 v[36:39], v[166:169], v[202:205], v[36:39]
	v_mfma_f32_16x16x32_bf16 v[32:35], v[186:189], v[202:205], v[32:35]
	v_mfma_f32_16x16x32_bf16 v[20:23], v[166:169], v[210:213], v[20:23]
	v_mfma_f32_16x16x32_bf16 v[16:19], v[186:189], v[210:213], v[16:19]
	v_mfma_f32_16x16x32_bf16 v[4:7], v[166:169], v[218:221], v[4:7]
	v_mfma_f32_16x16x32_bf16 v[0:3], v[186:189], v[218:221], v[0:3]
	s_setprio 0
	s_barrier
	s_add_i32 s92, s92, 2
	s_add_u32 vcc_lo, vcc_lo, 0x100
	s_addc_u32 vcc_hi, vcc_hi, 0
	s_cmp_gt_u32 s92, 13
	s_mov_b64 s[6:7], s[8:9]
	s_cbranch_scc0 .LBB0_228
	s_cmp_lt_u32 s78, 16
	s_cbranch_scc1 .LBB0_231
	s_and_b64 vcc, exec, s[82:83]
	s_cbranch_vccz .LBB0_231
	s_barrier

.LBB0_289:
	s_cmp_lt_u32 s78, 16
	s_cbranch_scc1 .LBB0_219
	s_andn2_b64 vcc, exec, s[0:1]
	s_cbranch_vccnz .LBB0_219
	s_barrier
	s_branch .LBB0_219
.LBB0_291:
	s_waitcnt vmcnt(0)
	s_and_b64 vcc, exec, s[82:83]
	s_cbranch_vccz .Lg1_na
	s_barrier
.Lg1_na:
	v_readlane_b32 s68, v251, 22
	v_readlane_b32 s97, v251, 28
	v_readlane_b32 s91, v251, 27
	v_readlane_b32 s96, v251, 34
	v_readlane_b32 s69, v251, 23
	v_readlane_b32 s83, v251, 26
	s_barrier
